# E24: pool unit MFMA block: 16 weight-fragment loads up front + counted waits; on E23
# baseline (speedup 1.0000x reference)
.LBB0_487:
	s_waitcnt lgkmcnt(0)
	s_or_b64 exec, exec, s[6:7]
	v_lshrrev_b32_e32 v6, 1, v10
	v_and_b32_e32 v6, 0x60, v6
	v_cmp_gt_u32_e32 vcc, s51, v6
	s_barrier
	s_and_saveexec_b64 s[6:7], vcc
	s_cbranch_execz .LBB0_521
	s_lshl_b32 s44, s58, 7
	v_and_b32_e32 v4, 0xffffffc0, v4
	v_add_u32_e32 v42, s44, v4
	v_or_b32_e32 v12, v42, v212
	v_ashrrev_i32_e32 v13, 31, v12
	v_lshlrev_b64 v[8:9], 8, v[12:13]
	v_lshl_add_u64 v[60:61], v[162:163], 0, v[8:9]
	v_or_b32_e32 v12, 32, v12
	v_ashrrev_i32_e32 v13, 31, v12
	v_lshlrev_b64 v[12:13], 8, v[12:13]
	v_lshl_add_u64 v[62:63], v[162:163], 0, v[12:13]
	v_or_b32_e32 v43, v6, v212
	v_mad_u32_u24 v64, v43, s3, v192
	global_load_dwordx4 v[88:91], v[60:61], off
	global_load_dwordx4 v[120:123], v[62:63], off
	global_load_dwordx4 v[92:95], v[60:61], off offset:32
	global_load_dwordx4 v[124:127], v[62:63], off offset:32
	global_load_dwordx4 v[96:99], v[60:61], off offset:64
	global_load_dwordx4 v[128:131], v[62:63], off offset:64
	global_load_dwordx4 v[100:103], v[60:61], off offset:96
	global_load_dwordx4 v[132:135], v[62:63], off offset:96
	global_load_dwordx4 v[104:107], v[60:61], off offset:128
	global_load_dwordx4 v[136:139], v[62:63], off offset:128
	global_load_dwordx4 v[108:111], v[60:61], off offset:160
	global_load_dwordx4 v[140:143], v[62:63], off offset:160
	global_load_dwordx4 v[112:115], v[60:61], off offset:192
	global_load_dwordx4 v[144:147], v[62:63], off offset:192
	global_load_dwordx4 v[116:119], v[60:61], off offset:224
	global_load_dwordx4 v[148:151], v[62:63], off offset:224
	ds_read_b128 v[44:47], v64 offset:39168
	ds_read_b128 v[48:51], v64 offset:39200
	v_cmp_gt_u32_e32 vcc, s51, v43
	s_waitcnt vmcnt(15) lgkmcnt(1)
	v_mfma_f32_32x32x16_bf16 v[22:37], v[88:91], v[44:47], 0
	s_waitcnt vmcnt(14)
	v_mfma_f32_32x32x16_bf16 v[6:21], v[120:123], v[44:47], 0
	ds_read_b128 v[44:47], v64 offset:39232
	s_waitcnt vmcnt(13) lgkmcnt(1)
	v_mfma_f32_32x32x16_bf16 v[22:37], v[92:95], v[48:51], v[22:37]
	s_waitcnt vmcnt(12)
	v_mfma_f32_32x32x16_bf16 v[6:21], v[124:127], v[48:51], v[6:21]
	ds_read_b128 v[48:51], v64 offset:39264
	s_waitcnt vmcnt(11) lgkmcnt(1)
	v_mfma_f32_32x32x16_bf16 v[22:37], v[96:99], v[44:47], v[22:37]
	s_waitcnt vmcnt(10)
	v_mfma_f32_32x32x16_bf16 v[6:21], v[128:131], v[44:47], v[6:21]
	ds_read_b128 v[44:47], v64 offset:39296
	s_waitcnt vmcnt(9) lgkmcnt(1)
	v_mfma_f32_32x32x16_bf16 v[22:37], v[100:103], v[48:51], v[22:37]
	s_waitcnt vmcnt(8)
	v_mfma_f32_32x32x16_bf16 v[6:21], v[132:135], v[48:51], v[6:21]
	ds_read_b128 v[48:51], v64 offset:39328
	s_waitcnt vmcnt(7) lgkmcnt(1)
	v_mfma_f32_32x32x16_bf16 v[22:37], v[104:107], v[44:47], v[22:37]
	s_waitcnt vmcnt(6)
	v_mfma_f32_32x32x16_bf16 v[6:21], v[136:139], v[44:47], v[6:21]
	ds_read_b128 v[44:47], v64 offset:39360
	s_waitcnt vmcnt(5) lgkmcnt(1)
	v_mfma_f32_32x32x16_bf16 v[22:37], v[108:111], v[48:51], v[22:37]
	s_waitcnt vmcnt(4)
	v_mfma_f32_32x32x16_bf16 v[6:21], v[140:143], v[48:51], v[6:21]
	ds_read_b128 v[48:51], v64 offset:39392
	s_waitcnt vmcnt(3) lgkmcnt(1)
	v_mfma_f32_32x32x16_bf16 v[22:37], v[112:115], v[44:47], v[22:37]
	s_waitcnt vmcnt(2)
	v_mfma_f32_32x32x16_bf16 v[6:21], v[144:147], v[44:47], v[6:21]
	s_waitcnt vmcnt(1) lgkmcnt(0)
	v_mfma_f32_32x32x16_bf16 v[22:37], v[116:119], v[48:51], v[22:37]
	s_waitcnt vmcnt(0)
	v_mfma_f32_32x32x16_bf16 v[6:21], v[148:151], v[48:51], v[6:21]
	s_and_b64 exec, exec, vcc
	s_cbranch_execz .LBB0_521
	s_add_i32 s45, s49, s50
	s_lshl_b32 s18, s44, 1
	s_lshl_b32 s4, s44, 2
	v_or_b32_e32 v38, v4, v216
	s_add_u32 s4, s8, s4
	s_addc_u32 s5, s9, 0
	v_ashrrev_i32_e32 v39, 31, v38
	v_lshl_add_u64 v[40:41], v[38:39], 2, s[4:5]
	global_load_dwordx4 v[44:47], v[40:41], off
	v_cndmask_b32_e64 v48, 0, 1, s[40:41]
	v_add_u32_e32 v4, s45, v43
	v_cmp_ne_u32_e64 s[4:5], 1, v48
	v_lshlrev_b64 v[48:49], 11, v[4:5]
	v_lshl_add_u64 v[48:49], s[24:25], 0, v[48:49]
	v_lshl_add_u64 v[48:49], v[48:49], 0, s[18:19]
	s_mov_b64 s[42:43], -1
	s_andn2_b64 vcc, exec, s[40:41]
	s_waitcnt vmcnt(0)
	v_pk_mul_f32 v[22:23], v[22:23], v[44:45]
	v_pk_mul_f32 v[24:25], v[24:25], v[46:47]
	v_cvt_pk_bf16_f32 v44, v22, v23
	v_cvt_pk_bf16_f32 v45, v24, v25
	v_lshl_add_u64 v[22:23], v[38:39], 1, v[48:49]
	s_cbranch_vccnz .LBB0_491
	s_mov_b64 s[42:43], 0
	global_store_dwordx2 v[22:23], v[44:45], off
